# in-proj GEMM K-loop LDS-DMA in SGPR-base + 32-bit VGPR offset form: 14 of 18 per-DMA 64-bit VALU adds removed from the load half
# baseline (speedup 1.0000x reference)
; #define PG8_STAGE(bufoff, gbase, voff) do { _Pragma("unroll") for (int _i = 0; _i < 2; ++_i) \
;         __builtin_amdgcn_global_load_lds((const unsigned*)((const char*)(gbase) + (voff)[_i]), (PG8_LAS unsigned*)(lds + (bufoff) + ldsw + _i * 8192), 16, 0, 0); } while (0)
; #define PG8_LDA(dst, b, h) do { _Pragma("unroll") for (int m = 0; m < 4; ++m) _Pragma("unroll") for (int k = 0; k < 2; ++k) dst[m][k] = *(const PG8_LAS bf16x8*)(lds + PG8_SA(b, h) + aoff + m * 2048 + k * 1024); } while (0)
; #define PG8_LDB(dst, b, h) do { _Pragma("unroll") for (int n = 0; n < 2; ++n) _Pragma("unroll") for (int k = 0; k < 2; ++k) dst[n][k] = *(const PG8_LAS bf16x8*)(lds + PG8_SB(b, h) + boff + n * 2048 + k * 1024); } while (0)
; #define PG8_MMA(ai, bj, At, Bt) do { __builtin_amdgcn_s_setprio(1); _Pragma("unroll") for (int m = 0; m < 4; ++m) _Pragma("unroll") for (int n = 0; n < 2; ++n) _Pragma("unroll") for (int k = 0; k < 2; ++k) \
;         acc[ai][bj][m][n] = __builtin_amdgcn_mfma_f32_16x16x32_bf16(Bt[n][k], At[m][k], acc[ai][bj][m][n], 0, 0, 0); __builtin_amdgcn_s_setprio(0); } while (0)
; #define PG8_WAIT_V(n) asm volatile("s_waitcnt vmcnt(" #n ")" ::: "memory")
; #define PG8_WAIT_L(n) asm volatile("s_waitcnt lgkmcnt(" #n ")" ::: "memory")
; #define PG8_BAR __builtin_amdgcn_s_barrier()
; #define PG8_SCHED __builtin_amdgcn_sched_barrier(0)
; template <class Epi, class Sched, bool ALIGN_EPI = false, bool SP2 = false>
; __device__ __forceinline__ void gemm_phase(PG8_LAS unsigned char* lds, const Gemm g, const Sched& S, const Epi& E) {
;     ...
;             PG8_LDB(B0, 0, 0); PG8_LDB(B1, 0, 1); PG8_SCHED; PG8_LDA(At, 0, 0); PG8_STAGE(PG8_SA(1, 1), a1 + hstepA, voffA);
;             PG8_WAIT_V(8); PG8_WAIT_L(0); PG8_BAR; PG8_MMA(0, 0, At, B0); PG8_MMA(0, 1, At, B1); PG8_BAR; PG8_SCHED;
;             PG8_LDA(At, 0, 1); PG8_STAGE(PG8_SB(0, 0), b2, voffB); PG8_STAGE(PG8_SB(0, 1), b2 + hstepB, voffB); PG8_STAGE(PG8_SA(0, 0), a2, voffA);
;             PG8_WAIT_V(8); PG8_WAIT_L(0); PG8_BAR; PG8_MMA(1, 0, At, B0); PG8_MMA(1, 1, At, B1); PG8_BAR; PG8_SCHED;
.LBB0_170:
	s_add_u32 s0, s6, 0x10000
	s_addc_u32 s1, s7, 0
	s_cmp_eq_u32 s47, 28
	s_cselect_b32 s24, s41, s0
	s_cselect_b32 s25, s40, s1
	s_cselect_b32 s22, s42, s43
	s_cselect_b32 s23, s31, s46
	s_add_u32 s8, s24, 0x8000
	s_addc_u32 s9, s25, 0
	s_add_i32 s49, 0, 0x10000
	s_add_i32 s56, 0, 0x14000
	v_add_u32_e32 v60, s49, v197
	v_add_u32_e32 v144, s56, v197
	ds_read_b128 v[48:51], v60
	ds_read_b128 v[52:55], v60 offset:1024
	ds_read_b128 v[56:59], v60 offset:2048
	ds_read_b128 v[60:63], v60 offset:3072
	ds_read_b128 v[200:203], v144
	ds_read_b128 v[204:207], v144 offset:1024
	ds_read_b128 v[208:211], v144 offset:2048
	ds_read_b128 v[212:215], v144 offset:3072
	v_lshl_add_u64 v[184:185], s[6:7], 0, v[172:173]
	s_add_i32 m0, s44, 0xc000
	ds_read_b128 v[216:219], v199
	ds_read_b128 v[220:223], v199 offset:1024
	ds_read_b128 v[224:227], v199 offset:2048
	ds_read_b128 v[228:231], v199 offset:3072
	ds_read_b128 v[232:235], v199 offset:4096
	ds_read_b128 v[236:239], v199 offset:5120
	ds_read_b128 v[240:243], v199 offset:6144
	ds_read_b128 v[244:247], v199 offset:7168
	global_load_lds_dwordx4 v[184:185], off
	v_lshl_add_u64 v[184:185], s[6:7], 0, v[174:175]
	s_add_i32 m0, s44, 0xe000
	s_nop 0
	global_load_lds_dwordx4 v[184:185], off
	s_waitcnt vmcnt(8)
	s_waitcnt lgkmcnt(0)
	s_barrier
	s_setprio 1
	s_waitcnt lgkmcnt(0)
	v_mfma_f32_16x16x32_bf16 v[140:143], v[48:51], v[216:219], v[140:143]
	v_mfma_f32_16x16x32_bf16 v[136:139], v[56:59], v[216:219], v[136:139]
	v_mfma_f32_16x16x32_bf16 v[124:127], v[48:51], v[224:227], v[124:127]
	v_mfma_f32_16x16x32_bf16 v[120:123], v[56:59], v[224:227], v[120:123]
	v_mfma_f32_16x16x32_bf16 v[108:111], v[48:51], v[232:235], v[108:111]
	v_mfma_f32_16x16x32_bf16 v[104:107], v[56:59], v[232:235], v[104:107]
	v_mfma_f32_16x16x32_bf16 v[92:95], v[48:51], v[240:243], v[92:95]
	v_mfma_f32_16x16x32_bf16 v[88:91], v[56:59], v[240:243], v[88:91]
	v_mfma_f32_16x16x32_bf16 v[140:143], v[52:55], v[220:223], v[140:143]
	v_mfma_f32_16x16x32_bf16 v[136:139], v[60:63], v[220:223], v[136:139]
	v_mfma_f32_16x16x32_bf16 v[124:127], v[52:55], v[228:231], v[124:127]
	v_mfma_f32_16x16x32_bf16 v[120:123], v[60:63], v[228:231], v[120:123]
	v_mfma_f32_16x16x32_bf16 v[108:111], v[52:55], v[236:239], v[108:111]
	v_mfma_f32_16x16x32_bf16 v[104:107], v[60:63], v[236:239], v[104:107]
	v_mfma_f32_16x16x32_bf16 v[92:95], v[52:55], v[244:247], v[92:95]
	v_mfma_f32_16x16x32_bf16 v[88:91], v[60:63], v[244:247], v[88:91]
	s_setprio 0
	s_setprio 1
	v_mfma_f32_16x16x32_bf16 v[132:135], v[200:203], v[216:219], v[132:135]
	v_mfma_f32_16x16x32_bf16 v[128:131], v[208:211], v[216:219], v[128:131]
	v_mfma_f32_16x16x32_bf16 v[116:119], v[200:203], v[224:227], v[116:119]
	v_mfma_f32_16x16x32_bf16 v[112:115], v[208:211], v[224:227], v[112:115]
	v_mfma_f32_16x16x32_bf16 v[100:103], v[200:203], v[232:235], v[100:103]
	v_mfma_f32_16x16x32_bf16 v[96:99], v[208:211], v[232:235], v[96:99]
	v_mfma_f32_16x16x32_bf16 v[84:87], v[200:203], v[240:243], v[84:87]
	v_mfma_f32_16x16x32_bf16 v[80:83], v[208:211], v[240:243], v[80:83]
	v_mfma_f32_16x16x32_bf16 v[132:135], v[204:207], v[220:223], v[132:135]
	v_mfma_f32_16x16x32_bf16 v[128:131], v[212:215], v[220:223], v[128:131]
	v_mfma_f32_16x16x32_bf16 v[116:119], v[204:207], v[228:231], v[116:119]
	v_mfma_f32_16x16x32_bf16 v[112:115], v[212:215], v[228:231], v[112:115]
	v_mfma_f32_16x16x32_bf16 v[100:103], v[204:207], v[236:239], v[100:103]
	v_mfma_f32_16x16x32_bf16 v[96:99], v[212:215], v[236:239], v[96:99]
	v_mfma_f32_16x16x32_bf16 v[84:87], v[204:207], v[244:247], v[84:87]
	v_mfma_f32_16x16x32_bf16 v[80:83], v[212:215], v[244:247], v[80:83]
	s_setprio 0
	s_barrier
	s_add_i32 s6, s49, s34
	s_mov_b32 m0, s6
	ds_read_b128 v[216:219], v199 offset:16384
	ds_read_b128 v[220:223], v199 offset:17408
	ds_read_b128 v[224:227], v199 offset:18432
	ds_read_b128 v[228:231], v199 offset:19456
	ds_read_b128 v[232:235], v199 offset:20480
	ds_read_b128 v[236:239], v199 offset:21504
	ds_read_b128 v[240:243], v199 offset:22528
	ds_read_b128 v[244:247], v199 offset:23552
	global_load_lds_dwordx4 v164, s[22:23]
	s_add_i32 m0, s6, 0x2000
	s_add_u32 s6, s22, 0x4000
	s_addc_u32 s7, s23, 0
	s_add_i32 s49, s56, s34
	global_load_lds_dwordx4 v166, s[22:23]
	s_mov_b32 m0, s49
	s_nop 0
	global_load_lds_dwordx4 v164, s[6:7]
	s_add_i32 m0, s49, 0x2000
	s_nop 0
	global_load_lds_dwordx4 v166, s[6:7]
	s_mov_b32 m0, s44
	s_nop 0
	global_load_lds_dwordx4 v164, s[24:25]
	s_mov_b32 m0, s45
	s_nop 0
	global_load_lds_dwordx4 v166, s[24:25]
	s_waitcnt vmcnt(8)
	s_waitcnt lgkmcnt(0)
	s_barrier
; #define PG8_STAGE(bufoff, gbase, voff) do { _Pragma("unroll") for (int _i = 0; _i < 2; ++_i) \
;         __builtin_amdgcn_global_load_lds((const unsigned*)((const char*)(gbase) + (voff)[_i]), (PG8_LAS unsigned*)(lds + (bufoff) + ldsw + _i * 8192), 16, 0, 0); } while (0)
; #define PG8_LDA(dst, b, h) do { _Pragma("unroll") for (int m = 0; m < 4; ++m) _Pragma("unroll") for (int k = 0; k < 2; ++k) dst[m][k] = *(const PG8_LAS bf16x8*)(lds + PG8_SA(b, h) + aoff + m * 2048 + k * 1024); } while (0)
; #define PG8_LDB(dst, b, h) do { _Pragma("unroll") for (int n = 0; n < 2; ++n) _Pragma("unroll") for (int k = 0; k < 2; ++k) dst[n][k] = *(const PG8_LAS bf16x8*)(lds + PG8_SB(b, h) + boff + n * 2048 + k * 1024); } while (0)
; #define PG8_MMA(ai, bj, At, Bt) do { __builtin_amdgcn_s_setprio(1); _Pragma("unroll") for (int m = 0; m < 4; ++m) _Pragma("unroll") for (int n = 0; n < 2; ++n) _Pragma("unroll") for (int k = 0; k < 2; ++k) \
;         acc[ai][bj][m][n] = __builtin_amdgcn_mfma_f32_16x16x32_bf16(Bt[n][k], At[m][k], acc[ai][bj][m][n], 0, 0, 0); __builtin_amdgcn_s_setprio(0); } while (0)
; #define PG8_WAIT_V(n) asm volatile("s_waitcnt vmcnt(" #n ")" ::: "memory")
; #define PG8_WAIT_L(n) asm volatile("s_waitcnt lgkmcnt(" #n ")" ::: "memory")
; #define PG8_BAR __builtin_amdgcn_s_barrier()
; #define PG8_SCHED __builtin_amdgcn_sched_barrier(0)
; template <class Epi, class Sched, bool ALIGN_EPI = false, bool SP2 = false>
; __device__ __forceinline__ void gemm_phase(PG8_LAS unsigned char* lds, const Gemm g, const Sched& S, const Epi& E) {
;     ...
;             PG8_WAIT_V(8); PG8_WAIT_L(0); PG8_BAR; PG8_MMA(1, 0, At, B0); PG8_MMA(1, 1, At, B1); PG8_BAR; PG8_SCHED;
;             PG8_LDB(B0, 1, 0); PG8_LDB(B1, 1, 1); PG8_SCHED; PG8_LDA(At, 1, 0); PG8_STAGE(PG8_SA(0, 1), a2 + hstepA, voffA);
;             PG8_WAIT_V(8); PG8_WAIT_L(0); PG8_BAR; PG8_MMA(0, 0, At, B0); PG8_MMA(0, 1, At, B1); PG8_BAR; PG8_SCHED;
	s_setprio 1
	s_waitcnt lgkmcnt(0)
	v_mfma_f32_16x16x32_bf16 v[76:79], v[48:51], v[216:219], v[76:79]
	v_mfma_f32_16x16x32_bf16 v[72:75], v[56:59], v[216:219], v[72:75]
	v_mfma_f32_16x16x32_bf16 v[44:47], v[48:51], v[224:227], v[44:47]
	v_mfma_f32_16x16x32_bf16 v[40:43], v[56:59], v[224:227], v[40:43]
	v_mfma_f32_16x16x32_bf16 v[28:31], v[48:51], v[232:235], v[28:31]
	v_mfma_f32_16x16x32_bf16 v[24:27], v[56:59], v[232:235], v[24:27]
	v_mfma_f32_16x16x32_bf16 v[12:15], v[48:51], v[240:243], v[12:15]
	v_mfma_f32_16x16x32_bf16 v[8:11], v[56:59], v[240:243], v[8:11]
	v_mfma_f32_16x16x32_bf16 v[76:79], v[52:55], v[220:223], v[76:79]
	v_mfma_f32_16x16x32_bf16 v[72:75], v[60:63], v[220:223], v[72:75]
	v_mfma_f32_16x16x32_bf16 v[44:47], v[52:55], v[228:231], v[44:47]
	v_mfma_f32_16x16x32_bf16 v[40:43], v[60:63], v[228:231], v[40:43]
	v_mfma_f32_16x16x32_bf16 v[28:31], v[52:55], v[236:239], v[28:31]
	v_mfma_f32_16x16x32_bf16 v[24:27], v[60:63], v[236:239], v[24:27]
	v_mfma_f32_16x16x32_bf16 v[12:15], v[52:55], v[244:247], v[12:15]
	v_mfma_f32_16x16x32_bf16 v[8:11], v[60:63], v[244:247], v[8:11]
	s_setprio 0
	s_setprio 1
	v_mfma_f32_16x16x32_bf16 v[36:39], v[200:203], v[224:227], v[36:39]
	v_mfma_f32_16x16x32_bf16 v[32:35], v[208:211], v[224:227], v[32:35]
	v_mfma_f32_16x16x32_bf16 v[20:23], v[200:203], v[232:235], v[20:23]
	v_mfma_f32_16x16x32_bf16 v[16:19], v[208:211], v[232:235], v[16:19]
	v_mfma_f32_16x16x32_bf16 v[4:7], v[200:203], v[240:243], v[4:7]
	v_mfma_f32_16x16x32_bf16 v[0:3], v[208:211], v[240:243], v[0:3]
	v_mfma_f32_16x16x32_bf16 v[48:51], v[200:203], v[216:219], v[68:71]
	v_mfma_f32_16x16x32_bf16 v[52:55], v[208:211], v[216:219], v[64:67]
	v_mfma_f32_16x16x32_bf16 v[36:39], v[204:207], v[228:231], v[36:39]
	v_mfma_f32_16x16x32_bf16 v[32:35], v[212:215], v[228:231], v[32:35]
	v_mfma_f32_16x16x32_bf16 v[20:23], v[204:207], v[236:239], v[20:23]
	v_mfma_f32_16x16x32_bf16 v[16:19], v[212:215], v[236:239], v[16:19]
	v_mfma_f32_16x16x32_bf16 v[4:7], v[204:207], v[244:247], v[4:7]
	v_mfma_f32_16x16x32_bf16 v[0:3], v[212:215], v[244:247], v[0:3]
	v_mfma_f32_16x16x32_bf16 v[48:51], v[204:207], v[220:223], v[48:51]
	v_mfma_f32_16x16x32_bf16 v[52:55], v[212:215], v[220:223], v[52:55]
	s_setprio 0
	s_barrier
	s_add_i32 s49, 0, 0x18000
	s_add_i32 s56, 0, 0x1c000
	v_add_u32_e32 v68, s49, v197
	v_add_u32_e32 v144, s56, v197
	ds_read_b128 v[56:59], v68
	ds_read_b128 v[60:63], v68 offset:1024
	ds_read_b128 v[64:67], v68 offset:2048
	ds_read_b128 v[68:71], v68 offset:3072
	ds_read_b128 v[200:203], v144
	ds_read_b128 v[204:207], v144 offset:1024
	ds_read_b128 v[208:211], v144 offset:2048
	ds_read_b128 v[212:215], v144 offset:3072
	s_add_u32 s6, s24, 0x4000
	s_addc_u32 s7, s25, 0
	s_mov_b32 m0, s54
	ds_read_b128 v[216:219], v199 offset:32768
	ds_read_b128 v[220:223], v199 offset:33792
	ds_read_b128 v[224:227], v199 offset:34816
	ds_read_b128 v[228:231], v199 offset:35840
	ds_read_b128 v[232:235], v199 offset:36864
	ds_read_b128 v[236:239], v199 offset:37888
	ds_read_b128 v[240:243], v199 offset:38912
	ds_read_b128 v[244:247], v199 offset:39936
	global_load_lds_dwordx4 v164, s[6:7]
	s_mov_b32 m0, s55
	s_nop 0
	global_load_lds_dwordx4 v166, s[6:7]
	s_waitcnt vmcnt(8)
	s_waitcnt lgkmcnt(0)
	s_barrier
	s_setprio 1
	s_waitcnt lgkmcnt(0)
	v_mfma_f32_16x16x32_bf16 v[140:143], v[56:59], v[216:219], v[140:143]
	v_mfma_f32_16x16x32_bf16 v[136:139], v[64:67], v[216:219], v[136:139]
	v_mfma_f32_16x16x32_bf16 v[124:127], v[56:59], v[224:227], v[124:127]
	v_mfma_f32_16x16x32_bf16 v[120:123], v[64:67], v[224:227], v[120:123]
	v_mfma_f32_16x16x32_bf16 v[108:111], v[56:59], v[232:235], v[108:111]
	v_mfma_f32_16x16x32_bf16 v[104:107], v[64:67], v[232:235], v[104:107]
	v_mfma_f32_16x16x32_bf16 v[92:95], v[56:59], v[240:243], v[92:95]
	v_mfma_f32_16x16x32_bf16 v[88:91], v[64:67], v[240:243], v[88:91]
	v_mfma_f32_16x16x32_bf16 v[140:143], v[60:63], v[220:223], v[140:143]
	v_mfma_f32_16x16x32_bf16 v[136:139], v[68:71], v[220:223], v[136:139]
	v_mfma_f32_16x16x32_bf16 v[124:127], v[60:63], v[228:231], v[124:127]
	v_mfma_f32_16x16x32_bf16 v[120:123], v[68:71], v[228:231], v[120:123]
	v_mfma_f32_16x16x32_bf16 v[108:111], v[60:63], v[236:239], v[108:111]
	v_mfma_f32_16x16x32_bf16 v[104:107], v[68:71], v[236:239], v[104:107]
	v_mfma_f32_16x16x32_bf16 v[92:95], v[60:63], v[244:247], v[92:95]
	v_mfma_f32_16x16x32_bf16 v[88:91], v[68:71], v[244:247], v[88:91]
	s_setprio 0
	s_setprio 1
	v_mfma_f32_16x16x32_bf16 v[132:135], v[200:203], v[216:219], v[132:135]
	v_mfma_f32_16x16x32_bf16 v[128:131], v[208:211], v[216:219], v[128:131]
	v_mfma_f32_16x16x32_bf16 v[116:119], v[200:203], v[224:227], v[116:119]
	v_mfma_f32_16x16x32_bf16 v[112:115], v[208:211], v[224:227], v[112:115]
	v_mfma_f32_16x16x32_bf16 v[100:103], v[200:203], v[232:235], v[100:103]
	v_mfma_f32_16x16x32_bf16 v[96:99], v[208:211], v[232:235], v[96:99]
	v_mfma_f32_16x16x32_bf16 v[84:87], v[200:203], v[240:243], v[84:87]
	v_mfma_f32_16x16x32_bf16 v[80:83], v[208:211], v[240:243], v[80:83]
	v_mfma_f32_16x16x32_bf16 v[132:135], v[204:207], v[220:223], v[132:135]
	v_mfma_f32_16x16x32_bf16 v[128:131], v[212:215], v[220:223], v[128:131]
	v_mfma_f32_16x16x32_bf16 v[116:119], v[204:207], v[228:231], v[116:119]
	v_mfma_f32_16x16x32_bf16 v[112:115], v[212:215], v[228:231], v[112:115]
	v_mfma_f32_16x16x32_bf16 v[100:103], v[204:207], v[236:239], v[100:103]
	v_mfma_f32_16x16x32_bf16 v[96:99], v[212:215], v[236:239], v[96:99]
	v_mfma_f32_16x16x32_bf16 v[84:87], v[204:207], v[244:247], v[84:87]
	v_mfma_f32_16x16x32_bf16 v[80:83], v[212:215], v[244:247], v[80:83]
	s_setprio 0
	s_barrier
; #define PG8_STAGE(bufoff, gbase, voff) do { _Pragma("unroll") for (int _i = 0; _i < 2; ++_i) \
;         __builtin_amdgcn_global_load_lds((const unsigned*)((const char*)(gbase) + (voff)[_i]), (PG8_LAS unsigned*)(lds + (bufoff) + ldsw + _i * 8192), 16, 0, 0); } while (0)
; #define PG8_LDA(dst, b, h) do { _Pragma("unroll") for (int m = 0; m < 4; ++m) _Pragma("unroll") for (int k = 0; k < 2; ++k) dst[m][k] = *(const PG8_LAS bf16x8*)(lds + PG8_SA(b, h) + aoff + m * 2048 + k * 1024); } while (0)
; #define PG8_MMA(ai, bj, At, Bt) do { __builtin_amdgcn_s_setprio(1); _Pragma("unroll") for (int m = 0; m < 4; ++m) _Pragma("unroll") for (int n = 0; n < 2; ++n) _Pragma("unroll") for (int k = 0; k < 2; ++k) \
;         acc[ai][bj][m][n] = __builtin_amdgcn_mfma_f32_16x16x32_bf16(Bt[n][k], At[m][k], acc[ai][bj][m][n], 0, 0, 0); __builtin_amdgcn_s_setprio(0); } while (0)
; #define PG8_WAIT_V(n) asm volatile("s_waitcnt vmcnt(" #n ")" ::: "memory")
; #define PG8_WAIT_L(n) asm volatile("s_waitcnt lgkmcnt(" #n ")" ::: "memory")
; #define PG8_BAR __builtin_amdgcn_s_barrier()
; #define PG8_SCHED __builtin_amdgcn_sched_barrier(0)
; template <class Epi, class Sched, bool ALIGN_EPI = false, bool SP2 = false>
; __device__ __forceinline__ void gemm_phase(PG8_LAS unsigned char* lds, const Gemm g, const Sched& S, const Epi& E) {
;     ...
;             PG8_WAIT_V(8); PG8_WAIT_L(0); PG8_BAR; PG8_MMA(0, 0, At, B0); PG8_MMA(0, 1, At, B1); PG8_BAR; PG8_SCHED;
;             PG8_LDA(At, 1, 1); PG8_STAGE(PG8_SB(1, 0), b3, voffB); PG8_STAGE(PG8_SB(1, 1), b3 + hstepB, voffB); PG8_STAGE(PG8_SA(1, 0), a3, voffA);
;             PG8_WAIT_V(8); PG8_WAIT_L(0); PG8_BAR; PG8_MMA(1, 0, At, B0); PG8_MMA(1, 1, At, B1); PG8_BAR; PG8_SCHED;
	s_add_u32 s6, s22, 0x8000
	s_addc_u32 s7, s23, 0
	s_add_i32 s24, s49, s34
	s_mov_b32 m0, s24
	ds_read_b128 v[216:219], v199 offset:49152
	ds_read_b128 v[220:223], v199 offset:50176
	ds_read_b128 v[224:227], v199 offset:51200
	ds_read_b128 v[228:231], v199 offset:52224
	ds_read_b128 v[232:235], v199 offset:53248
	ds_read_b128 v[236:239], v199 offset:54272
	ds_read_b128 v[240:243], v199 offset:55296
	ds_read_b128 v[244:247], v199 offset:56320
	global_load_lds_dwordx4 v164, s[6:7]
	s_add_i32 m0, s24, 0x2000
	s_nop 0
	global_load_lds_dwordx4 v166, s[6:7]
	s_add_u32 s6, s22, 0xc000
	s_addc_u32 s7, s23, 0
	s_add_i32 s22, s56, s34
	s_mov_b32 m0, s22
	s_nop 0
	global_load_lds_dwordx4 v164, s[6:7]
	s_add_i32 m0, s22, 0x2000
	s_nop 0
	global_load_lds_dwordx4 v166, s[6:7]
	s_mov_b32 m0, s73
	s_nop 0
	global_load_lds_dwordx4 v164, s[8:9]
	s_mov_b32 m0, s76
	s_nop 0
	global_load_lds_dwordx4 v166, s[8:9]
	s_waitcnt vmcnt(8)
	s_waitcnt lgkmcnt(0)
	s_barrier
	s_setprio 1
	s_waitcnt lgkmcnt(0)
	v_mfma_f32_16x16x32_bf16 v[76:79], v[56:59], v[216:219], v[76:79]
	v_mfma_f32_16x16x32_bf16 v[72:75], v[64:67], v[216:219], v[72:75]
	v_mfma_f32_16x16x32_bf16 v[44:47], v[56:59], v[224:227], v[44:47]
	v_mfma_f32_16x16x32_bf16 v[40:43], v[64:67], v[224:227], v[40:43]
	v_mfma_f32_16x16x32_bf16 v[28:31], v[56:59], v[232:235], v[28:31]
	v_mfma_f32_16x16x32_bf16 v[24:27], v[64:67], v[232:235], v[24:27]
	v_mfma_f32_16x16x32_bf16 v[12:15], v[56:59], v[240:243], v[12:15]
	v_mfma_f32_16x16x32_bf16 v[8:11], v[64:67], v[240:243], v[8:11]
	v_mfma_f32_16x16x32_bf16 v[76:79], v[60:63], v[220:223], v[76:79]
	v_mfma_f32_16x16x32_bf16 v[72:75], v[68:71], v[220:223], v[72:75]
	v_mfma_f32_16x16x32_bf16 v[44:47], v[60:63], v[228:231], v[44:47]
	v_mfma_f32_16x16x32_bf16 v[40:43], v[68:71], v[228:231], v[40:43]
	v_mfma_f32_16x16x32_bf16 v[28:31], v[60:63], v[236:239], v[28:31]
	v_mfma_f32_16x16x32_bf16 v[24:27], v[68:71], v[236:239], v[24:27]
	v_mfma_f32_16x16x32_bf16 v[12:15], v[60:63], v[244:247], v[12:15]
	v_mfma_f32_16x16x32_bf16 v[8:11], v[68:71], v[244:247], v[8:11]
	s_setprio 0
	s_setprio 1
	v_mfma_f32_16x16x32_bf16 v[48:51], v[200:203], v[216:219], v[48:51]
	v_mfma_f32_16x16x32_bf16 v[68:71], v[204:207], v[220:223], v[48:51]
	v_mfma_f32_16x16x32_bf16 v[48:51], v[208:211], v[216:219], v[52:55]
	v_mfma_f32_16x16x32_bf16 v[36:39], v[200:203], v[224:227], v[36:39]
	v_mfma_f32_16x16x32_bf16 v[32:35], v[208:211], v[224:227], v[32:35]
	v_mfma_f32_16x16x32_bf16 v[20:23], v[200:203], v[232:235], v[20:23]
	v_mfma_f32_16x16x32_bf16 v[16:19], v[208:211], v[232:235], v[16:19]
	v_mfma_f32_16x16x32_bf16 v[4:7], v[200:203], v[240:243], v[4:7]
	v_mfma_f32_16x16x32_bf16 v[0:3], v[208:211], v[240:243], v[0:3]
	v_mfma_f32_16x16x32_bf16 v[64:67], v[212:215], v[220:223], v[48:51]
	v_mfma_f32_16x16x32_bf16 v[36:39], v[204:207], v[228:231], v[36:39]
	v_mfma_f32_16x16x32_bf16 v[32:35], v[212:215], v[228:231], v[32:35]
	v_mfma_f32_16x16x32_bf16 v[20:23], v[204:207], v[236:239], v[20:23]
	v_mfma_f32_16x16x32_bf16 v[16:19], v[212:215], v[236:239], v[16:19]
	v_mfma_f32_16x16x32_bf16 v[4:7], v[204:207], v[244:247], v[4:7]
	v_mfma_f32_16x16x32_bf16 v[0:3], v[212:215], v[244:247], v[0:3]
	s_setprio 0
	s_barrier
	s_add_i32 s47, s47, 2
	s_add_u32 s43, s43, 0x10000
	s_addc_u32 s46, s46, 0
	s_cmp_gt_u32 s47, 29
	s_mov_b64 s[6:7], s[0:1]
	s_cbranch_scc0 .LBB0_170
	s_and_b64 vcc, exec, s[20:21]
	s_cbranch_vccz .LBB0_173
	s_barrier
